# gdn_chunk_prep l2-norm: LDS reads batched eight at a time (was one exposed LDS round trip per float pair); gate prefetch reordered
# baseline (speedup 1.0000x reference)
.LBB0_365:
	s_or_b64 exec, exec, s[86:87]
	s_waitcnt vmcnt(59)
	v_lshlrev_b32_e32 v0, 16, v8
	v_cndmask_b32_e64 v1, 0, v0, s[44:45]
	s_waitcnt vmcnt(57)
	v_lshlrev_b32_e32 v0, 16, v9
	v_cndmask_b32_e64 v8, 0, v0, s[46:47]
	s_waitcnt vmcnt(55)
	v_lshlrev_b32_e32 v0, 16, v49
	v_cndmask_b32_e64 v9, 0, v0, s[48:49]
	s_waitcnt vmcnt(53)
	v_lshlrev_b32_e32 v0, 16, v50
	v_cndmask_b32_e64 v49, 0, v0, s[50:51]
	s_waitcnt vmcnt(50)
	v_lshlrev_b32_e32 v0, 16, v51
	v_cndmask_b32_e64 v50, 0, v0, s[52:53]
	s_waitcnt vmcnt(47)
	v_lshlrev_b32_e32 v0, 16, v52
	s_waitcnt vmcnt(3)
	v_mul_f32_e32 v2, v65, v70
	v_cndmask_b32_e64 v51, 0, v0, s[54:55]
	v_lshlrev_b32_e32 v0, 16, v53
	s_waitcnt vmcnt(2)
	v_fmac_f32_e32 v2, v1, v66
	v_cndmask_b32_e64 v52, 0, v0, s[56:57]
	v_lshlrev_b32_e32 v0, 16, v54
	s_waitcnt vmcnt(1)
	v_fmac_f32_e32 v2, v8, v67
	v_cndmask_b32_e64 v53, 0, v0, s[58:59]
	v_lshlrev_b32_e32 v0, 16, v55
	s_waitcnt vmcnt(0)
	s_load_dwordx2 s[2:3], s[36:37], 0x28
	v_mov_b32_e32 v216, v68
	v_mov_b32_e32 v217, 0
	v_lshl_add_u64 v[216:217], s[40:41], 0, v[216:217]
	v_lshlrev_b64 v[216:217], 7, v[216:217]
	v_lshl_add_u64 v[216:217], s[80:81], 0, v[216:217]
	s_lshl_b32 vcc_lo, s26, 2
	s_mov_b32 vcc_hi, 0
	v_lshl_add_u64 v[216:217], v[216:217], 0, vcc
	s_mov_b64 vcc, 0x10000000
	v_lshl_add_u64 v[216:217], v[216:217], 0, vcc
	global_load_dword v200, v[216:217], off offset:16
	global_load_dword v201, v[216:217], off
	s_or_b32 vcc_lo, s26, s94
	s_lshl_b32 vcc_lo, vcc_lo, 2
	s_add_u32 s92, s92, vcc_lo
	s_addc_u32 s93, s93, 0
	global_load_dword v202, v129, s[92:93]
	s_mov_b64 vcc, 0x1000
	v_lshl_add_u64 v[212:213], v[6:7], 0, vcc
	s_mov_b64 vcc, 0x2000
	v_lshl_add_u64 v[214:215], v[6:7], 0, vcc
	global_load_dword v204, v[6:7], off offset:1024
	global_load_dword v205, v[212:213], off
	global_load_dword v206, v[212:213], off offset:3072
	global_load_dword v207, v[214:215], off offset:2048
	global_load_dword v208, v[6:7], off offset:2048
	global_load_dword v209, v[212:213], off offset:1024
	global_load_dword v210, v[214:215], off
	global_load_dword v211, v[214:215], off offset:3072
	s_waitcnt lgkmcnt(0)
	s_or_b32 vcc_lo, s26, s94
	s_lshl_b32 vcc_lo, vcc_lo, 2
	s_add_u32 s2, s2, vcc_lo
	s_addc_u32 s3, s3, 0
	global_load_dword v203, v129, s[2:3]
	v_fmac_f32_e32 v2, v9, v69
	v_cndmask_b32_e64 v54, 0, v0, s[60:61]
	v_lshlrev_b32_e32 v0, 16, v56
	v_mul_f32_e32 v3, 0xbfb8aa3b, v2
	v_cndmask_b32_e64 v55, 0, v0, s[62:63]
	v_lshlrev_b32_e32 v0, 16, v57
	v_exp_f32_e32 v3, v3
	v_cndmask_b32_e64 v56, 0, v0, s[64:65]
	v_lshlrev_b32_e32 v0, 16, v58
	v_cndmask_b32_e64 v57, 0, v0, s[66:67]
	v_lshlrev_b32_e32 v0, 16, v59
	v_cndmask_b32_e64 v58, 0, v0, s[68:69]
	v_lshlrev_b32_e32 v0, 16, v60
	v_cndmask_b32_e64 v59, 0, v0, s[70:71]
	v_lshlrev_b32_e32 v0, 16, v61
	v_add_f32_e32 v3, 1.0, v3
	v_cndmask_b32_e64 v60, 0, v0, s[72:73]
	v_lshlrev_b32_e32 v0, 16, v62
	v_rcp_f32_e32 v3, v3
	v_cndmask_b32_e64 v61, 0, v0, s[74:75]
	v_lshlrev_b32_e32 v0, 16, v63
	s_and_b32 s2, s90, 0xfffffc00
	s_lshl_b32 s3, s26, 8
	v_cndmask_b32_e64 v62, 0, v0, s[76:77]
	v_lshlrev_b32_e32 v0, 16, v64
	s_or_b32 s2, s3, s2
	v_cndmask_b32_e64 v63, 0, v0, s[78:79]
	v_lshlrev_b32_e32 v0, 2, v34
	s_or_b32 s86, s2, s27
	v_mul_f32_e32 v64, v2, v3
	v_mad_u64_u32 v[2:3], s[2:3], v5, s33, v[0:1]
	v_mul_f32_e32 v3, v8, v66
	v_fmac_f32_e32 v3, v1, v65
	v_fmac_f32_e32 v3, v9, v67
	v_fmac_f32_e32 v3, v49, v69
	v_mul_f32_e32 v1, 0xbfb8aa3b, v3
	v_exp_f32_e32 v1, v1
	v_lshlrev_b32_e32 v30, 16, v30
	v_lshlrev_b32_e32 v29, 16, v29
	v_cndmask_b32_e64 v30, 0, v30, s[44:45]
	v_add_f32_e32 v1, 1.0, v1
	v_rcp_f32_e32 v1, v1
	v_cndmask_b32_e64 v29, 0, v29, s[42:43]
	v_lshlrev_b32_e32 v31, 16, v31
	v_cndmask_b32_e64 v31, 0, v31, s[46:47]
	v_mul_f32_e32 v1, v3, v1
	ds_write2_b32 v2, v64, v1 offset1:65
	v_mul_f32_e32 v1, v9, v66
	v_fmac_f32_e32 v1, v8, v65
	v_fmac_f32_e32 v1, v49, v67
	v_fmac_f32_e32 v1, v50, v69
	v_mul_f32_e32 v3, 0xbfb8aa3b, v1
	v_exp_f32_e32 v3, v3
	v_lshlrev_b32_e32 v32, 16, v32
	v_cndmask_b32_e64 v32, 0, v32, s[48:49]
	v_lshlrev_b32_e32 v33, 16, v33
	v_add_f32_e32 v3, 1.0, v3
	v_rcp_f32_e32 v3, v3
	v_cndmask_b32_e64 v33, 0, v33, s[50:51]
	v_lshlrev_b32_e32 v35, 16, v35
	v_cndmask_b32_e64 v35, 0, v35, s[52:53]
	v_mul_f32_e32 v1, v1, v3
	v_mul_f32_e32 v3, v49, v66
	v_fmac_f32_e32 v3, v9, v65
	v_fmac_f32_e32 v3, v50, v67
	v_fmac_f32_e32 v3, v51, v69
	v_mul_f32_e32 v5, 0xbfb8aa3b, v3
	v_exp_f32_e32 v5, v5
	v_lshlrev_b32_e32 v36, 16, v36
	v_cndmask_b32_e64 v36, 0, v36, s[54:55]
	v_lshlrev_b32_e32 v37, 16, v37
	v_add_f32_e32 v5, 1.0, v5
	v_rcp_f32_e32 v5, v5
	v_cndmask_b32_e64 v37, 0, v37, s[56:57]
	v_lshlrev_b32_e32 v38, 16, v38
	v_cndmask_b32_e64 v38, 0, v38, s[58:59]
	v_mul_f32_e32 v3, v3, v5
	ds_write2_b32 v2, v1, v3 offset0:130 offset1:195
	v_mul_f32_e32 v1, v50, v66
	v_fmac_f32_e32 v1, v49, v65
	v_fmac_f32_e32 v1, v51, v67
	v_fmac_f32_e32 v1, v52, v69
	v_mul_f32_e32 v3, 0xbfb8aa3b, v1
	v_exp_f32_e32 v3, v3
	v_lshlrev_b32_e32 v39, 16, v39
	v_cndmask_b32_e64 v39, 0, v39, s[60:61]
	v_lshlrev_b32_e32 v40, 16, v40
	v_add_f32_e32 v3, 1.0, v3
	v_rcp_f32_e32 v3, v3
	v_cndmask_b32_e64 v40, 0, v40, s[62:63]
	v_lshlrev_b32_e32 v41, 16, v41
	v_cndmask_b32_e64 v41, 0, v41, s[64:65]
	v_mul_f32_e32 v1, v1, v3
	v_mul_f32_e32 v3, v51, v66
	v_fmac_f32_e32 v3, v50, v65
	v_fmac_f32_e32 v3, v52, v67
	v_fmac_f32_e32 v3, v53, v69
	v_mul_f32_e32 v5, 0xbfb8aa3b, v3
	v_exp_f32_e32 v5, v5
	v_lshlrev_b32_e32 v42, 16, v42
	v_cndmask_b32_e64 v42, 0, v42, s[66:67]
	v_lshlrev_b32_e32 v43, 16, v43
	v_add_f32_e32 v5, 1.0, v5
	v_rcp_f32_e32 v5, v5
	v_cndmask_b32_e64 v43, 0, v43, s[68:69]
	v_lshlrev_b32_e32 v44, 16, v44
	v_cndmask_b32_e64 v44, 0, v44, s[70:71]
	v_mul_f32_e32 v3, v3, v5
	v_add_u32_e32 v5, 0x400, v2
	ds_write2_b32 v5, v1, v3 offset0:4 offset1:69
	v_mul_f32_e32 v1, v52, v66
	v_fmac_f32_e32 v1, v51, v65
	v_fmac_f32_e32 v1, v53, v67
	v_fmac_f32_e32 v1, v54, v69
	v_mul_f32_e32 v3, 0xbfb8aa3b, v1
	v_exp_f32_e32 v3, v3
	v_lshlrev_b32_e32 v45, 16, v45
	v_cndmask_b32_e64 v45, 0, v45, s[72:73]
	v_lshlrev_b32_e32 v46, 16, v46
	v_add_f32_e32 v3, 1.0, v3
	v_rcp_f32_e32 v3, v3
	v_cndmask_b32_e64 v46, 0, v46, s[74:75]
	v_lshlrev_b32_e32 v47, 16, v47
	v_cndmask_b32_e64 v47, 0, v47, s[76:77]
	v_mul_f32_e32 v1, v1, v3
	v_mul_f32_e32 v3, v53, v66
	v_fmac_f32_e32 v3, v52, v65
	v_fmac_f32_e32 v3, v54, v67
	v_fmac_f32_e32 v3, v55, v69
	v_mul_f32_e32 v8, 0xbfb8aa3b, v3
	v_exp_f32_e32 v8, v8
	v_lshlrev_b32_e32 v48, 16, v48
	v_cndmask_b32_e64 v48, 0, v48, s[78:79]
	s_ashr_i32 s87, s86, 31
	v_add_f32_e32 v8, 1.0, v8
	v_rcp_f32_e32 v8, v8
	s_nop 0
	v_mul_f32_e32 v3, v3, v8
	ds_write2_b32 v5, v1, v3 offset0:134 offset1:199
	v_mul_f32_e32 v1, v54, v66
	v_fmac_f32_e32 v1, v53, v65
	v_fmac_f32_e32 v1, v55, v67
	v_fmac_f32_e32 v1, v56, v69
	v_mul_f32_e32 v3, 0xbfb8aa3b, v1
	v_exp_f32_e32 v3, v3
	s_nop 0
	v_add_f32_e32 v3, 1.0, v3
	v_rcp_f32_e32 v3, v3
	s_nop 0
	v_mul_f32_e32 v1, v1, v3
	v_mul_f32_e32 v3, v55, v66
	v_fmac_f32_e32 v3, v54, v65
	v_fmac_f32_e32 v3, v56, v67
	v_fmac_f32_e32 v3, v57, v69
	v_mul_f32_e32 v5, 0xbfb8aa3b, v3
	v_exp_f32_e32 v5, v5
	s_nop 0
	v_add_f32_e32 v5, 1.0, v5
	v_rcp_f32_e32 v5, v5
	s_nop 0
	v_mul_f32_e32 v3, v3, v5
	v_add_u32_e32 v5, 0x800, v2
	ds_write2_b32 v5, v1, v3 offset0:8 offset1:73
	v_mul_f32_e32 v1, v56, v66
	v_fmac_f32_e32 v1, v55, v65
	v_fmac_f32_e32 v1, v57, v67
	v_fmac_f32_e32 v1, v58, v69
	v_mul_f32_e32 v3, 0xbfb8aa3b, v1
	v_exp_f32_e32 v3, v3
	s_nop 0
	v_add_f32_e32 v3, 1.0, v3
	v_rcp_f32_e32 v3, v3
	s_nop 0
	v_mul_f32_e32 v1, v1, v3
	v_mul_f32_e32 v3, v57, v66
	v_fmac_f32_e32 v3, v56, v65
	v_fmac_f32_e32 v3, v58, v67
	v_fmac_f32_e32 v3, v59, v69
	v_mul_f32_e32 v8, 0xbfb8aa3b, v3
	v_exp_f32_e32 v8, v8
	s_nop 0
	v_add_f32_e32 v8, 1.0, v8
	v_rcp_f32_e32 v8, v8
	s_nop 0
	v_mul_f32_e32 v3, v3, v8
	ds_write2_b32 v5, v1, v3 offset0:138 offset1:203
	v_mul_f32_e32 v1, v58, v66
	v_fmac_f32_e32 v1, v57, v65
	v_fmac_f32_e32 v1, v59, v67
	v_fmac_f32_e32 v1, v60, v69
	v_mul_f32_e32 v3, 0xbfb8aa3b, v1
	v_exp_f32_e32 v3, v3
	s_nop 0
	v_add_f32_e32 v3, 1.0, v3
	v_rcp_f32_e32 v3, v3
	s_nop 0
	v_mul_f32_e32 v1, v1, v3
	v_mul_f32_e32 v3, v59, v66
	v_fmac_f32_e32 v3, v58, v65
	v_fmac_f32_e32 v3, v60, v67
	v_fmac_f32_e32 v3, v61, v69
	v_mul_f32_e32 v5, 0xbfb8aa3b, v3
	v_exp_f32_e32 v5, v5
	s_nop 0
	v_add_f32_e32 v5, 1.0, v5
	v_rcp_f32_e32 v5, v5
	s_nop 0
	v_mul_f32_e32 v3, v3, v5
	v_add_u32_e32 v5, 0xc00, v2
	ds_write2_b32 v5, v1, v3 offset0:12 offset1:77
	v_mul_f32_e32 v1, v60, v66
	v_fmac_f32_e32 v1, v59, v65
	v_fmac_f32_e32 v1, v61, v67
	v_fmac_f32_e32 v1, v62, v69
	v_mul_f32_e32 v3, 0xbfb8aa3b, v1
	v_exp_f32_e32 v3, v3
	s_nop 0
	v_add_f32_e32 v3, 1.0, v3
	v_rcp_f32_e32 v3, v3
	s_nop 0
	v_mul_f32_e32 v1, v1, v3
	ds_write_b32 v2, v1 offset:3640
	v_mul_f32_e32 v1, v61, v66
	v_fmac_f32_e32 v1, v60, v65
	v_fmac_f32_e32 v1, v62, v67
	v_fmac_f32_e32 v1, v63, v69
	v_mul_f32_e32 v3, 0xbfb8aa3b, v1
	v_exp_f32_e32 v3, v3
	s_nop 0
	v_add_f32_e32 v3, 1.0, v3
	v_rcp_f32_e32 v3, v3
	s_nop 0
	v_mul_f32_e32 v1, v1, v3
	v_mad_u64_u32 v[4:5], s[2:3], v4, s33, v[0:1]
	s_mov_b64 s[2:3], 0x400
	ds_write_b32 v4, v1
	v_lshl_add_u64 v[8:9], v[6:7], 0, s[2:3]
	s_movk_i32 s2, 0x1000
	s_waitcnt vmcnt(0)
	v_add_co_u32_e32 v8, vcc, s2, v6
	s_movk_i32 s2, 0x2000
	s_nop 0
	v_addc_co_u32_e32 v9, vcc, 0, v7, vcc
	v_add_co_u32_e32 v8, vcc, s2, v6
	v_mul_f32_e32 v50, v30, v205
	v_addc_co_u32_e32 v9, vcc, 0, v7, vcc
	v_fmac_f32_e32 v50, v29, v204
	s_mov_b64 vcc, 0x800
	v_fmac_f32_e32 v50, v31, v206
	v_fmac_f32_e32 v50, v32, v207
	v_mul_f32_e32 v29, 0xbfb8aa3b, v50
	v_exp_f32_e32 v29, v29
	s_nop 0
	v_add_f32_e32 v29, 1.0, v29
	v_rcp_f32_e32 v29, v29
	s_nop 0
	v_mul_f32_e32 v29, v50, v29
	v_mul_f32_e32 v50, v31, v205
	v_fmac_f32_e32 v50, v30, v204
	v_fmac_f32_e32 v50, v32, v206
	v_fmac_f32_e32 v50, v33, v207
	v_mul_f32_e32 v30, 0xbfb8aa3b, v50
	v_exp_f32_e32 v30, v30
	s_nop 0
	v_add_f32_e32 v30, 1.0, v30
	v_rcp_f32_e32 v30, v30
	s_nop 0
	v_mul_f32_e32 v30, v50, v30
	v_add_u32_e32 v50, 0x4000, v2
	ds_write2_b32 v50, v29, v30 offset0:64 offset1:129
	v_mul_f32_e32 v29, v32, v205
	v_fmac_f32_e32 v29, v31, v204
	v_fmac_f32_e32 v29, v33, v206
	v_fmac_f32_e32 v29, v35, v207
	v_mul_f32_e32 v30, 0xbfb8aa3b, v29
	v_exp_f32_e32 v30, v30
	s_nop 0
	v_add_f32_e32 v30, 1.0, v30
	v_rcp_f32_e32 v30, v30
	s_nop 0
	v_mul_f32_e32 v29, v29, v30
	v_mul_f32_e32 v30, v33, v205
	v_fmac_f32_e32 v30, v32, v204
	v_fmac_f32_e32 v30, v35, v206
	v_fmac_f32_e32 v30, v36, v207
	v_mul_f32_e32 v31, 0xbfb8aa3b, v30
	v_exp_f32_e32 v31, v31
	s_nop 0
	v_add_f32_e32 v31, 1.0, v31
	v_rcp_f32_e32 v31, v31
	s_nop 0
	v_mul_f32_e32 v30, v30, v31
	v_add_u32_e32 v31, 0x4200, v2
	ds_write2_b32 v31, v29, v30 offset0:66 offset1:131
	v_mul_f32_e32 v29, v35, v205
	v_fmac_f32_e32 v29, v33, v204
	v_fmac_f32_e32 v29, v36, v206
	v_fmac_f32_e32 v29, v37, v207
	v_mul_f32_e32 v30, 0xbfb8aa3b, v29
	v_exp_f32_e32 v30, v30
	s_nop 0
	v_add_f32_e32 v30, 1.0, v30
	v_rcp_f32_e32 v30, v30
	s_nop 0
	v_mul_f32_e32 v29, v29, v30
	v_mul_f32_e32 v30, v36, v205
	v_fmac_f32_e32 v30, v35, v204
	v_fmac_f32_e32 v30, v37, v206
	v_fmac_f32_e32 v30, v38, v207
	v_mul_f32_e32 v31, 0xbfb8aa3b, v30
	v_exp_f32_e32 v31, v31
	s_nop 0
	v_add_f32_e32 v31, 1.0, v31
	v_rcp_f32_e32 v31, v31
	s_nop 0
	v_mul_f32_e32 v30, v30, v31
	v_add_u32_e32 v31, 0x4400, v2
	ds_write2_b32 v31, v29, v30 offset0:68 offset1:133
	v_mul_f32_e32 v29, v37, v205
	v_fmac_f32_e32 v29, v36, v204
	v_fmac_f32_e32 v29, v38, v206
	v_fmac_f32_e32 v29, v39, v207
	v_mul_f32_e32 v30, 0xbfb8aa3b, v29
	v_exp_f32_e32 v30, v30
	s_nop 0
	v_add_f32_e32 v30, 1.0, v30
	v_rcp_f32_e32 v30, v30
	s_nop 0
	v_mul_f32_e32 v29, v29, v30
	v_mul_f32_e32 v30, v38, v205
	v_fmac_f32_e32 v30, v37, v204
	v_fmac_f32_e32 v30, v39, v206
	v_fmac_f32_e32 v30, v40, v207
	v_mul_f32_e32 v31, 0xbfb8aa3b, v30
	v_exp_f32_e32 v31, v31
	s_nop 0
	v_add_f32_e32 v31, 1.0, v31
	v_rcp_f32_e32 v31, v31
	s_nop 0
	v_mul_f32_e32 v30, v30, v31
	v_add_u32_e32 v31, 0x4600, v2
	ds_write2_b32 v31, v29, v30 offset0:70 offset1:135
	v_mul_f32_e32 v29, v39, v205
	v_fmac_f32_e32 v29, v38, v204
	v_fmac_f32_e32 v29, v40, v206
	v_fmac_f32_e32 v29, v41, v207
	v_mul_f32_e32 v30, 0xbfb8aa3b, v29
	v_exp_f32_e32 v30, v30
	s_nop 0
	v_add_f32_e32 v30, 1.0, v30
	v_rcp_f32_e32 v30, v30
	s_nop 0
	v_mul_f32_e32 v29, v29, v30
	v_mul_f32_e32 v30, v40, v205
	v_fmac_f32_e32 v30, v39, v204
	v_fmac_f32_e32 v30, v41, v206
	v_fmac_f32_e32 v30, v42, v207
	v_mul_f32_e32 v31, 0xbfb8aa3b, v30
	v_exp_f32_e32 v31, v31
	s_nop 0
	v_add_f32_e32 v31, 1.0, v31
	v_rcp_f32_e32 v31, v31
	s_nop 0
	v_mul_f32_e32 v30, v30, v31
	v_add_u32_e32 v31, 0x4800, v2
	ds_write2_b32 v31, v29, v30 offset0:72 offset1:137
	v_mul_f32_e32 v29, v41, v205
	v_fmac_f32_e32 v29, v40, v204
	v_fmac_f32_e32 v29, v42, v206
	v_fmac_f32_e32 v29, v43, v207
	v_mul_f32_e32 v30, 0xbfb8aa3b, v29
	v_exp_f32_e32 v30, v30
	s_nop 0
	v_add_f32_e32 v30, 1.0, v30
	v_rcp_f32_e32 v30, v30
	s_nop 0
	v_mul_f32_e32 v29, v29, v30
	v_mul_f32_e32 v30, v42, v205
	v_fmac_f32_e32 v30, v41, v204
	v_fmac_f32_e32 v30, v43, v206
	v_fmac_f32_e32 v30, v44, v207
	v_mul_f32_e32 v31, 0xbfb8aa3b, v30
	v_exp_f32_e32 v31, v31
	s_nop 0
	v_add_f32_e32 v31, 1.0, v31
	v_rcp_f32_e32 v31, v31
	s_nop 0
	v_mul_f32_e32 v30, v30, v31
	v_add_u32_e32 v31, 0x4a00, v2
	ds_write2_b32 v31, v29, v30 offset0:74 offset1:139
	v_mul_f32_e32 v29, v43, v205
	v_fmac_f32_e32 v29, v42, v204
	v_fmac_f32_e32 v29, v44, v206
	v_fmac_f32_e32 v29, v45, v207
	v_mul_f32_e32 v30, 0xbfb8aa3b, v29
	v_exp_f32_e32 v30, v30
	s_nop 0
	v_add_f32_e32 v30, 1.0, v30
	v_rcp_f32_e32 v30, v30
	s_nop 0
	v_mul_f32_e32 v29, v29, v30
	v_mul_f32_e32 v30, v44, v205
	v_fmac_f32_e32 v30, v43, v204
	v_fmac_f32_e32 v30, v45, v206
	v_fmac_f32_e32 v30, v46, v207
	v_mul_f32_e32 v31, 0xbfb8aa3b, v30
	v_exp_f32_e32 v31, v31
	s_nop 0
	v_add_f32_e32 v31, 1.0, v31
	v_rcp_f32_e32 v31, v31
	s_nop 0
	v_mul_f32_e32 v30, v30, v31
	v_add_u32_e32 v31, 0x4c00, v2
	ds_write2_b32 v31, v29, v30 offset0:76 offset1:141
	v_mul_f32_e32 v29, v45, v205
	v_mul_f32_e32 v3, v46, v205
	v_fmac_f32_e32 v29, v44, v204
	v_fmac_f32_e32 v3, v45, v204
	v_fmac_f32_e32 v29, v46, v206
	v_fmac_f32_e32 v3, v47, v206
	v_fmac_f32_e32 v29, v47, v207
	v_fmac_f32_e32 v3, v48, v207
	v_mul_f32_e32 v30, 0xbfb8aa3b, v29
	v_mul_f32_e32 v1, 0xbfb8aa3b, v3
	v_exp_f32_e32 v30, v30
	v_exp_f32_e32 v1, v1
	v_add_f32_e32 v30, 1.0, v30
	v_add_f32_e32 v1, 1.0, v1
	v_rcp_f32_e32 v30, v30
	v_rcp_f32_e32 v1, v1
	v_mul_f32_e32 v29, v29, v30
	v_mul_f32_e32 v1, v3, v1
	ds_write_b32 v2, v29 offset:20280
	ds_write_b32 v4, v1 offset:16640
	v_lshl_add_u64 v[30:31], v[6:7], 0, vcc
	s_waitcnt vmcnt(0)
	s_nop 0
	v_lshlrev_b32_e32 v8, 16, v11
	v_lshlrev_b32_e32 v7, 16, v10
	v_cndmask_b32_e64 v8, 0, v8, s[44:45]
	v_cndmask_b32_e64 v7, 0, v7, s[42:43]
	v_lshlrev_b32_e32 v9, 16, v12
	v_lshlrev_b32_e32 v11, 16, v14
	v_lshlrev_b32_e32 v14, 16, v17
	v_lshlrev_b32_e32 v17, 16, v20
	v_lshlrev_b32_e32 v20, 16, v23
	v_lshlrev_b32_e32 v23, 16, v26
	v_cndmask_b32_e64 v9, 0, v9, s[46:47]
	v_lshlrev_b32_e32 v10, 16, v13
	v_cndmask_b32_e64 v10, 0, v10, s[48:49]
	v_cndmask_b32_e64 v11, 0, v11, s[50:51]
	v_lshlrev_b32_e32 v12, 16, v15
	v_cndmask_b32_e64 v12, 0, v12, s[52:53]
	v_lshlrev_b32_e32 v13, 16, v16
	v_cndmask_b32_e64 v13, 0, v13, s[54:55]
	v_cndmask_b32_e64 v14, 0, v14, s[56:57]
	v_lshlrev_b32_e32 v15, 16, v18
	v_cndmask_b32_e64 v15, 0, v15, s[58:59]
	v_lshlrev_b32_e32 v16, 16, v19
	v_cndmask_b32_e64 v16, 0, v16, s[60:61]
	v_cndmask_b32_e64 v17, 0, v17, s[62:63]
	v_lshlrev_b32_e32 v18, 16, v21
	v_cndmask_b32_e64 v18, 0, v18, s[64:65]
	v_lshlrev_b32_e32 v19, 16, v22
	v_cndmask_b32_e64 v19, 0, v19, s[66:67]
	v_cndmask_b32_e64 v20, 0, v20, s[68:69]
	v_lshlrev_b32_e32 v21, 16, v24
	v_cndmask_b32_e64 v21, 0, v21, s[70:71]
	v_lshlrev_b32_e32 v22, 16, v25
	v_cndmask_b32_e64 v22, 0, v22, s[72:73]
	v_cndmask_b32_e64 v23, 0, v23, s[74:75]
	v_lshlrev_b32_e32 v24, 16, v27
	v_cndmask_b32_e64 v24, 0, v24, s[76:77]
	v_lshlrev_b32_e32 v25, 16, v28
	v_cndmask_b32_e64 v25, 0, v25, s[78:79]
	v_cmp_lt_i32_e64 s[42:43], 63, v68
	v_cmp_gt_i32_e64 s[44:45], 64, v68
	v_mul_f32_e32 v26, v8, v209
	v_fmac_f32_e32 v26, v7, v208
	v_fmac_f32_e32 v26, v9, v210
	v_fmac_f32_e32 v26, v10, v211
	v_mul_f32_e32 v7, 0xbfb8aa3b, v26
	v_exp_f32_e32 v7, v7
	s_nop 0
	v_add_f32_e32 v7, 1.0, v7
	v_rcp_f32_e32 v7, v7
	s_nop 0
	v_mul_f32_e32 v7, v26, v7
	v_mul_f32_e32 v26, v9, v209
	v_fmac_f32_e32 v26, v8, v208
	v_fmac_f32_e32 v26, v10, v210
	v_fmac_f32_e32 v26, v11, v211
	v_mul_f32_e32 v8, 0xbfb8aa3b, v26
	v_exp_f32_e32 v8, v8
	s_nop 0
	v_add_f32_e32 v8, 1.0, v8
	v_rcp_f32_e32 v8, v8
	s_nop 0
	v_mul_f32_e32 v8, v26, v8
	v_add_u32_e32 v26, 0x8000, v2
	ds_write2_b32 v26, v7, v8 offset0:128 offset1:193
	v_mul_f32_e32 v7, v10, v209
	v_fmac_f32_e32 v7, v9, v208
	v_fmac_f32_e32 v7, v11, v210
	v_fmac_f32_e32 v7, v12, v211
	v_mul_f32_e32 v8, 0xbfb8aa3b, v7
	v_exp_f32_e32 v8, v8
	s_nop 0
	v_add_f32_e32 v8, 1.0, v8
	v_rcp_f32_e32 v8, v8
	s_nop 0
	v_mul_f32_e32 v7, v7, v8
	v_mul_f32_e32 v8, v11, v209
	v_fmac_f32_e32 v8, v10, v208
	v_fmac_f32_e32 v8, v12, v210
	v_fmac_f32_e32 v8, v13, v211
	v_mul_f32_e32 v9, 0xbfb8aa3b, v8
	v_exp_f32_e32 v9, v9
	s_nop 0
	v_add_f32_e32 v9, 1.0, v9
	v_rcp_f32_e32 v9, v9
	s_nop 0
	v_mul_f32_e32 v8, v8, v9
	v_add_u32_e32 v9, 0x8400, v2
	ds_write2_b32 v9, v7, v8 offset0:2 offset1:67
	v_mul_f32_e32 v7, v12, v209
	v_fmac_f32_e32 v7, v11, v208
	v_fmac_f32_e32 v7, v13, v210
	v_fmac_f32_e32 v7, v14, v211
	v_mul_f32_e32 v8, 0xbfb8aa3b, v7
	v_exp_f32_e32 v8, v8
	s_nop 0
	v_add_f32_e32 v8, 1.0, v8
	v_rcp_f32_e32 v8, v8
	s_nop 0
	v_mul_f32_e32 v7, v7, v8
	v_mul_f32_e32 v8, v13, v209
	v_fmac_f32_e32 v8, v12, v208
	v_fmac_f32_e32 v8, v14, v210
	v_fmac_f32_e32 v8, v15, v211
	v_mul_f32_e32 v10, 0xbfb8aa3b, v8
	v_exp_f32_e32 v10, v10
	s_nop 0
	v_add_f32_e32 v10, 1.0, v10
	v_rcp_f32_e32 v10, v10
	s_nop 0
	v_mul_f32_e32 v8, v8, v10
	ds_write2_b32 v9, v7, v8 offset0:132 offset1:197
	v_mul_f32_e32 v7, v14, v209
	v_fmac_f32_e32 v7, v13, v208
	v_fmac_f32_e32 v7, v15, v210
	v_fmac_f32_e32 v7, v16, v211
	v_mul_f32_e32 v8, 0xbfb8aa3b, v7
	v_exp_f32_e32 v8, v8
	s_nop 0
	v_add_f32_e32 v8, 1.0, v8
	v_rcp_f32_e32 v8, v8
	s_nop 0
	v_mul_f32_e32 v7, v7, v8
	v_mul_f32_e32 v8, v15, v209
	v_fmac_f32_e32 v8, v14, v208
	v_fmac_f32_e32 v8, v16, v210
	v_fmac_f32_e32 v8, v17, v211
	v_mul_f32_e32 v9, 0xbfb8aa3b, v8
	v_exp_f32_e32 v9, v9
	s_nop 0
	v_add_f32_e32 v9, 1.0, v9
	v_rcp_f32_e32 v9, v9
	s_nop 0
	v_mul_f32_e32 v8, v8, v9
	v_add_u32_e32 v9, 0x8800, v2
	ds_write2_b32 v9, v7, v8 offset0:6 offset1:71
	v_mul_f32_e32 v7, v16, v209
	v_fmac_f32_e32 v7, v15, v208
	v_fmac_f32_e32 v7, v17, v210
	v_fmac_f32_e32 v7, v18, v211
	v_mul_f32_e32 v8, 0xbfb8aa3b, v7
	v_exp_f32_e32 v8, v8
	s_nop 0
	v_add_f32_e32 v8, 1.0, v8
	v_rcp_f32_e32 v8, v8
	s_nop 0
	v_mul_f32_e32 v7, v7, v8
	v_mul_f32_e32 v8, v17, v209
	v_fmac_f32_e32 v8, v16, v208
	v_fmac_f32_e32 v8, v18, v210
	v_fmac_f32_e32 v8, v19, v211
	v_mul_f32_e32 v10, 0xbfb8aa3b, v8
	v_exp_f32_e32 v10, v10
	s_nop 0
	v_add_f32_e32 v10, 1.0, v10
	v_rcp_f32_e32 v10, v10
	s_nop 0
	v_mul_f32_e32 v8, v8, v10
	ds_write2_b32 v9, v7, v8 offset0:136 offset1:201
	v_mul_f32_e32 v7, v18, v209
	v_fmac_f32_e32 v7, v17, v208
	v_fmac_f32_e32 v7, v19, v210
	v_fmac_f32_e32 v7, v20, v211
	v_mul_f32_e32 v8, 0xbfb8aa3b, v7
	v_exp_f32_e32 v8, v8
	s_nop 0
	v_add_f32_e32 v8, 1.0, v8
	v_rcp_f32_e32 v8, v8
	s_nop 0
	v_mul_f32_e32 v7, v7, v8
	v_mul_f32_e32 v8, v19, v209
	v_fmac_f32_e32 v8, v18, v208
	v_fmac_f32_e32 v8, v20, v210
	v_fmac_f32_e32 v8, v21, v211
	v_mul_f32_e32 v9, 0xbfb8aa3b, v8
	v_exp_f32_e32 v9, v9
	s_nop 0
	v_add_f32_e32 v9, 1.0, v9
	v_rcp_f32_e32 v9, v9
	s_nop 0
	v_mul_f32_e32 v8, v8, v9
	v_add_u32_e32 v9, 0x8c00, v2
	ds_write2_b32 v9, v7, v8 offset0:10 offset1:75
	v_mul_f32_e32 v7, v20, v209
	v_fmac_f32_e32 v7, v19, v208
	v_fmac_f32_e32 v7, v21, v210
	v_fmac_f32_e32 v7, v22, v211
	v_mul_f32_e32 v8, 0xbfb8aa3b, v7
	v_exp_f32_e32 v8, v8
	s_nop 0
	v_add_f32_e32 v8, 1.0, v8
	v_rcp_f32_e32 v8, v8
	s_nop 0
	v_mul_f32_e32 v7, v7, v8
	v_mul_f32_e32 v8, v21, v209
	v_fmac_f32_e32 v8, v20, v208
	v_fmac_f32_e32 v8, v22, v210
	v_fmac_f32_e32 v8, v23, v211
	v_mul_f32_e32 v10, 0xbfb8aa3b, v8
	v_exp_f32_e32 v10, v10
	s_nop 0
	v_add_f32_e32 v10, 1.0, v10
	v_rcp_f32_e32 v10, v10
	s_nop 0
	v_mul_f32_e32 v8, v8, v10
	ds_write2_b32 v9, v7, v8 offset0:140 offset1:205
	v_mul_f32_e32 v7, v22, v209
	v_fmac_f32_e32 v7, v21, v208
	v_fmac_f32_e32 v7, v23, v210
	v_fmac_f32_e32 v7, v24, v211
	v_mul_f32_e32 v8, 0xbfb8aa3b, v7
	v_exp_f32_e32 v8, v8
	s_nop 0
	v_add_f32_e32 v8, 1.0, v8
	v_rcp_f32_e32 v8, v8
	s_nop 0
	v_mul_f32_e32 v7, v7, v8
	ds_write_b32 v2, v7 offset:36920
	v_mul_f32_e32 v2, v23, v209
	v_fmac_f32_e32 v2, v22, v208
	v_fmac_f32_e32 v2, v24, v210
	v_fmac_f32_e32 v2, v25, v211
	v_mul_f32_e32 v1, 0xbfb8aa3b, v2
	v_exp_f32_e32 v1, v1
	s_nop 0
	v_add_f32_e32 v1, 1.0, v1
	v_rcp_f32_e32 v1, v1
	s_nop 0
	v_mul_f32_e32 v1, v2, v1
	ds_write_b32 v4, v1 offset:33280
	v_lshlrev_b32_e32 v1, 2, v68
	v_mov_b32_e32 v3, v210
	v_mov_b32_e32 v5, v209
	v_mov_b32_e32 v6, v211
	v_mov_b32_e32 v49, v207
	s_and_saveexec_b64 s[46:47], s[44:45]
	s_cbranch_execz .LBB0_368
	v_ashrrev_i32_e32 v69, 31, v68
	v_lshl_add_u64 v[2:3], s[40:41], 0, v[68:69]
	v_lshlrev_b64 v[2:3], 7, v[2:3]
	v_lshl_add_u64 v[2:3], s[80:81], 0, v[2:3]
	s_lshl_b32 s84, s26, 2
	v_lshl_add_u64 v[2:3], v[2:3], 0, s[84:85]
	s_or_b32 s84, s26, s94
	s_mov_b64 s[2:3], 0x10000000
	s_lshl_b64 s[40:41], s[84:85], 2
	v_lshl_add_u64 v[4:5], v[2:3], 0, s[2:3]
	s_waitcnt lgkmcnt(0)
	s_add_u32 s2, s50, s40
	v_add_co_u32_e32 v2, vcc, 0x10000000, v2
	s_addc_u32 s3, s51, s41
	s_nop 0
	v_addc_co_u32_e32 v3, vcc, 0, v3, vcc
	v_add_u32_e32 v10, -1, v229
	v_and_b32_e32 v3, 64, v229
	s_add_u32 s2, s48, s40
	s_addc_u32 s3, s49, s41
	s_waitcnt vmcnt(0)
	s_mov_b32 s2, 0xbfb8aa3b
	s_mov_b32 s3, 0x3f2aaaab
	v_cmp_lt_i32_e32 vcc, v10, v3
	s_mov_b32 s26, 0x3f317218
	v_mov_b32_e32 v7, 0x3ecc95a3
	v_cndmask_b32_e32 v10, v10, v229, vcc
	s_mov_b32 s27, 0x7f800000
	v_mov_b32_e32 v8, 0x7fc00000
	v_mov_b32_e32 v9, 0xff800000
	s_mov_b32 s28, 0x33800000
	v_lshlrev_b32_e32 v10, 2, v10
	v_mul_f32_e32 v2, 0xbfb8aa3b, v201
	v_exp_f32_e32 v2, v2
	v_add_f32_e32 v4, v200, v202
	v_mul_f32_e64 v5, |v4|, s2
	v_exp_f32_e32 v11, v5
	v_max_f32_e32 v12, 0, v4
	v_mul_f32_e32 v4, 0x3fb8aa3b, v203
	v_exp_f32_e32 v6, v4
	v_add_f32_e32 v13, 1.0, v11
	v_add_f32_e32 v14, -1.0, v13
	v_frexp_mant_f32_e32 v15, v13
	v_cvt_f64_f32_e32 v[4:5], v13
	v_sub_f32_e32 v16, v14, v13
	v_frexp_exp_i32_f64_e32 v4, v[4:5]
	v_cmp_gt_f32_e32 vcc, s3, v15
	v_sub_f32_e32 v14, v11, v14
	v_add_f32_e32 v5, 1.0, v16
	v_subbrev_co_u32_e32 v4, vcc, 0, v4, vcc
	v_add_f32_e32 v5, v14, v5
	v_sub_u32_e32 v14, 0, v4
	v_cvt_f32_i32_e32 v4, v4
	v_ldexp_f32 v13, v13, v14
	v_ldexp_f32 v5, v5, v14
	v_add_f32_e32 v14, -1.0, v13
	v_add_f32_e32 v15, 1.0, v13
	v_add_f32_e32 v16, 1.0, v14
	v_add_f32_e32 v17, -1.0, v15
	v_sub_f32_e32 v16, v13, v16
	v_sub_f32_e32 v13, v13, v17
	v_mul_f32_e32 v17, 0x3f317218, v4
	v_add_f32_e32 v16, v5, v16
	v_add_f32_e32 v5, v5, v13
	v_fma_f32 v13, v4, s26, -v17
	v_add_f32_e32 v18, v14, v16
	v_add_f32_e32 v19, v15, v5
	v_fmac_f32_e32 v13, 0xb102e308, v4
	v_sub_f32_e32 v4, v18, v14
	v_sub_f32_e32 v14, v19, v15
	v_rcp_f32_e32 v15, v19
	v_add_f32_e32 v20, v17, v13
	v_sub_f32_e32 v5, v5, v14
	v_sub_f32_e32 v14, v20, v17
	v_sub_f32_e32 v13, v13, v14
	v_mul_f32_e32 v14, v18, v15
	v_sub_f32_e32 v4, v16, v4
	v_mul_f32_e32 v16, v19, v14
	v_fma_f32 v17, v14, v19, -v16
	v_fmac_f32_e32 v17, v14, v5
	v_add_f32_e32 v21, v16, v17
	v_sub_f32_e32 v22, v18, v21
	v_sub_f32_e32 v16, v21, v16
	v_sub_f32_e32 v18, v18, v22
	v_sub_f32_e32 v16, v16, v17
	v_sub_f32_e32 v17, v18, v21
	v_add_f32_e32 v4, v4, v17
	v_add_f32_e32 v4, v16, v4
	v_add_f32_e32 v16, v22, v4
	v_mul_f32_e32 v17, v15, v16
	v_sub_f32_e32 v18, v22, v16
	v_mul_f32_e32 v21, v19, v17
	v_add_f32_e32 v4, v4, v18
	v_add_f32_e32 v18, v14, v17
	v_fma_f32 v19, v17, v19, -v21
	v_sub_f32_e32 v14, v18, v14
	v_fmac_f32_e32 v19, v17, v5
	v_sub_f32_e32 v5, v17, v14
	v_add_f32_e32 v14, v21, v19
	v_sub_f32_e32 v17, v14, v21
	v_sub_f32_e32 v21, v16, v14
	v_sub_f32_e32 v16, v16, v21
	v_sub_f32_e32 v14, v16, v14
	v_sub_f32_e32 v17, v17, v19
	v_add_f32_e32 v4, v4, v14
	v_add_f32_e32 v4, v17, v4
	v_add_f32_e32 v4, v21, v4
	v_mul_f32_e32 v4, v15, v4
	v_add_f32_e32 v4, v5, v4
	v_add_f32_e32 v5, v18, v4
	v_mul_f32_e32 v14, v5, v5
	v_fmamk_f32 v7, v14, 0x3e9b6dac, v7
	v_sub_f32_e32 v15, v5, v18
	v_ldexp_f32 v16, v5, 1
	v_mul_f32_e32 v5, v5, v14
	v_fmaak_f32 v7, v14, v7, 0x3f2aaada
	v_mul_f32_e32 v5, v5, v7
	v_add_f32_e32 v7, v16, v5
	v_sub_f32_e32 v4, v4, v15
	v_sub_f32_e32 v14, v7, v16
	v_ldexp_f32 v4, v4, 1
	v_sub_f32_e32 v5, v5, v14
	v_add_f32_e32 v4, v4, v5
	v_add_f32_e32 v5, v7, v4
	v_sub_f32_e32 v7, v5, v7
	v_add_f32_e32 v14, v20, v5
	v_sub_f32_e32 v4, v4, v7
	v_sub_f32_e32 v7, v14, v20
	v_sub_f32_e32 v15, v14, v7
	v_sub_f32_e32 v5, v5, v7
	v_add_f32_e32 v7, v13, v4
	v_sub_f32_e32 v15, v20, v15
	v_sub_f32_e32 v16, v7, v13
	v_add_f32_e32 v5, v5, v15
	v_sub_f32_e32 v15, v7, v16
	v_add_f32_e32 v5, v7, v5
	v_sub_f32_e32 v4, v4, v16
	v_sub_f32_e32 v13, v13, v15
	v_add_f32_e32 v7, v14, v5
	v_add_f32_e32 v4, v4, v13
	v_sub_f32_e32 v13, v7, v14
	v_sub_f32_e32 v5, v5, v13
	v_add_f32_e32 v4, v4, v5
	v_add_f32_e32 v4, v7, v4
	v_cmp_neq_f32_e32 vcc, s27, v11
	v_add_f32_e32 v2, 1.0, v2
	s_nop 0
	v_cndmask_b32_e32 v4, v228, v4, vcc
	v_cmp_ngt_f32_e32 vcc, -1.0, v11
	s_nop 1
	v_cndmask_b32_e32 v4, v8, v4, vcc
	v_cmp_neq_f32_e32 vcc, -1.0, v11
	v_add_u32_e32 v8, -2, v229
	s_nop 0
	v_cndmask_b32_e32 v4, v9, v4, vcc
	v_cmp_lt_f32_e64 vcc, |v11|, s28
	s_nop 1
	v_cndmask_b32_e32 v4, v4, v11, vcc
	v_add_f32_e32 v4, v12, v4
	v_mul_f32_e64 v5, v4, -v6
	ds_bpermute_b32 v7, v10, v5
	v_cmp_lt_i32_e32 vcc, v8, v3
	s_waitcnt lgkmcnt(0)
	v_fma_f32 v4, v4, -v6, v7
	v_cndmask_b32_e32 v8, v8, v229, vcc
	v_cmp_eq_u32_e32 vcc, 0, v34
	v_lshlrev_b32_e32 v8, 2, v8
	v_add_u32_e32 v6, -4, v229
	v_cndmask_b32_e32 v4, v4, v5, vcc
	ds_bpermute_b32 v5, v8, v4
	v_cmp_lt_i32_e32 vcc, v6, v3
	s_waitcnt lgkmcnt(0)
	v_add_f32_e32 v5, v4, v5
	v_cndmask_b32_e32 v6, v6, v229, vcc
	v_cmp_gt_u32_e32 vcc, 2, v34
	s_nop 1
	v_cndmask_b32_e32 v4, v5, v4, vcc
	v_lshlrev_b32_e32 v5, 2, v6
	ds_bpermute_b32 v5, v5, v4
	v_add_u32_e32 v6, -8, v229
	v_cmp_gt_u32_e32 vcc, 4, v34
	s_waitcnt lgkmcnt(0)
	v_add_f32_e32 v5, v4, v5
	v_cndmask_b32_e32 v4, v5, v4, vcc
	v_cmp_lt_i32_e32 vcc, v6, v3
	s_nop 1
	v_cndmask_b32_e32 v5, v6, v229, vcc
	v_lshlrev_b32_e32 v5, 2, v5
	ds_bpermute_b32 v5, v5, v4
	v_add_u32_e32 v6, -16, v229
	v_cmp_gt_u32_e32 vcc, 8, v34
	s_waitcnt lgkmcnt(0)
	v_add_f32_e32 v5, v4, v5
	v_cndmask_b32_e32 v4, v5, v4, vcc
	v_cmp_lt_i32_e32 vcc, v6, v3
	s_nop 1
	v_cndmask_b32_e32 v5, v6, v229, vcc
	v_lshlrev_b32_e32 v5, 2, v5
	ds_bpermute_b32 v5, v5, v4
	v_cmp_gt_u32_e32 vcc, 16, v34
	s_waitcnt lgkmcnt(0)
	v_add_f32_e32 v5, v4, v5
	v_cndmask_b32_e32 v4, v5, v4, vcc
	v_subrev_u32_e32 v5, 32, v229
	v_cmp_lt_i32_e32 vcc, v5, v3
	s_nop 1
	v_cndmask_b32_e32 v3, v5, v229, vcc
	v_lshlrev_b32_e32 v3, 2, v3
	ds_bpermute_b32 v3, v3, v4
	v_cmp_gt_u32_e32 vcc, 32, v34
	v_add_u32_e32 v5, 0x10300, v1
	s_waitcnt lgkmcnt(0)
	v_add_f32_e32 v3, v4, v3
	v_cndmask_b32_e32 v3, v3, v4, vcc
	v_rcp_f32_e32 v4, v2
	v_mul_f32_e32 v2, 0x3fb8aa3b, v3
	v_exp_f32_e32 v2, v2
	ds_write_b32 v5, v3
	v_add_u32_e32 v3, 0x10400, v1
	ds_write_b32 v3, v4
	v_add_u32_e32 v3, 0x10500, v1
	ds_write_b32 v3, v2
	v_mul_f32_e32 v3, v4, v2
	v_add_u32_e32 v4, 0x10600, v1
	v_cmp_eq_u32_e32 vcc, 63, v68
	ds_write_b32 v4, v3
	s_and_b64 exec, exec, vcc
	s_cbranch_execz .LBB0_368
	s_lshl_b64 s[2:3], s[86:87], 2
	s_add_u32 s2, s80, s2
	s_addc_u32 s3, s81, s3
	global_store_dword v225, v2, s[2:3]

.LBB0_370:
	ds_read2_b32 v[130:131], v4 offset1:1
	ds_read2_b32 v[132:133], v4 offset0:2 offset1:3
	ds_read2_b32 v[134:135], v4 offset0:4 offset1:5
	ds_read2_b32 v[136:137], v4 offset0:6 offset1:7
	ds_read2_b32 v[138:139], v4 offset0:8 offset1:9
	ds_read2_b32 v[140:141], v4 offset0:10 offset1:11
	ds_read2_b32 v[142:143], v4 offset0:12 offset1:13
	ds_read2_b32 v[144:145], v4 offset0:14 offset1:15
	s_waitcnt lgkmcnt(0)
	ds_read2_b32 v[146:147], v4 offset0:16 offset1:17
	ds_read2_b32 v[148:149], v4 offset0:18 offset1:19
	ds_read2_b32 v[150:151], v4 offset0:20 offset1:21
	ds_read2_b32 v[152:153], v4 offset0:22 offset1:23
	ds_read2_b32 v[154:155], v4 offset0:24 offset1:25
	ds_read2_b32 v[156:157], v4 offset0:26 offset1:27
	ds_read2_b32 v[158:159], v4 offset0:28 offset1:29
	ds_read2_b32 v[160:161], v4 offset0:30 offset1:31
	v_fmac_f32_e32 v2, v130, v130
	v_fmac_f32_e32 v2, v131, v131
	v_fmac_f32_e32 v2, v132, v132
	v_fmac_f32_e32 v2, v133, v133
	v_fmac_f32_e32 v2, v134, v134
	v_fmac_f32_e32 v2, v135, v135
	v_fmac_f32_e32 v2, v136, v136
	v_fmac_f32_e32 v2, v137, v137
	v_fmac_f32_e32 v2, v138, v138
	v_fmac_f32_e32 v2, v139, v139
	v_fmac_f32_e32 v2, v140, v140
	v_fmac_f32_e32 v2, v141, v141
	v_fmac_f32_e32 v2, v142, v142
	v_fmac_f32_e32 v2, v143, v143
	v_fmac_f32_e32 v2, v144, v144
	v_fmac_f32_e32 v2, v145, v145
	s_waitcnt lgkmcnt(0)
	ds_read2_b32 v[130:131], v4 offset0:32 offset1:33
	ds_read2_b32 v[132:133], v4 offset0:34 offset1:35
	ds_read2_b32 v[134:135], v4 offset0:36 offset1:37
	ds_read2_b32 v[136:137], v4 offset0:38 offset1:39
	ds_read2_b32 v[138:139], v4 offset0:40 offset1:41
	ds_read2_b32 v[140:141], v4 offset0:42 offset1:43
	ds_read2_b32 v[142:143], v4 offset0:44 offset1:45
	ds_read2_b32 v[144:145], v4 offset0:46 offset1:47
	v_fmac_f32_e32 v2, v146, v146
	v_fmac_f32_e32 v2, v147, v147
	v_fmac_f32_e32 v2, v148, v148
	v_fmac_f32_e32 v2, v149, v149
	v_fmac_f32_e32 v2, v150, v150
	v_fmac_f32_e32 v2, v151, v151
	v_fmac_f32_e32 v2, v152, v152
	v_fmac_f32_e32 v2, v153, v153
	v_fmac_f32_e32 v2, v154, v154
	v_fmac_f32_e32 v2, v155, v155
	v_fmac_f32_e32 v2, v156, v156
	v_fmac_f32_e32 v2, v157, v157
	v_fmac_f32_e32 v2, v158, v158
	v_fmac_f32_e32 v2, v159, v159
	v_fmac_f32_e32 v2, v160, v160
	v_fmac_f32_e32 v2, v161, v161
	s_waitcnt lgkmcnt(0)
	ds_read2_b32 v[146:147], v4 offset0:48 offset1:49
	ds_read2_b32 v[148:149], v4 offset0:50 offset1:51
	ds_read2_b32 v[150:151], v4 offset0:52 offset1:53
	ds_read2_b32 v[152:153], v4 offset0:54 offset1:55
	ds_read2_b32 v[154:155], v4 offset0:56 offset1:57
	ds_read2_b32 v[156:157], v4 offset0:58 offset1:59
	ds_read2_b32 v[158:159], v4 offset0:60 offset1:61
	ds_read2_b32 v[160:161], v4 offset0:62 offset1:63
	v_fmac_f32_e32 v2, v130, v130
	v_fmac_f32_e32 v2, v131, v131
	v_fmac_f32_e32 v2, v132, v132
	v_fmac_f32_e32 v2, v133, v133
	v_fmac_f32_e32 v2, v134, v134
	v_fmac_f32_e32 v2, v135, v135
	v_fmac_f32_e32 v2, v136, v136
	v_fmac_f32_e32 v2, v137, v137
	v_fmac_f32_e32 v2, v138, v138
	v_fmac_f32_e32 v2, v139, v139
	v_fmac_f32_e32 v2, v140, v140
	v_fmac_f32_e32 v2, v141, v141
	v_fmac_f32_e32 v2, v142, v142
	v_fmac_f32_e32 v2, v143, v143
	v_fmac_f32_e32 v2, v144, v144
	v_fmac_f32_e32 v2, v145, v145
	s_waitcnt lgkmcnt(0)
	v_fmac_f32_e32 v2, v146, v146
	v_fmac_f32_e32 v2, v147, v147
	v_fmac_f32_e32 v2, v148, v148
	v_fmac_f32_e32 v2, v149, v149
	v_fmac_f32_e32 v2, v150, v150
	v_fmac_f32_e32 v2, v151, v151
	v_fmac_f32_e32 v2, v152, v152
	v_fmac_f32_e32 v2, v153, v153
	v_fmac_f32_e32 v2, v154, v154
	v_fmac_f32_e32 v2, v155, v155
	v_fmac_f32_e32 v2, v156, v156
	v_fmac_f32_e32 v2, v157, v157
	v_fmac_f32_e32 v2, v158, v158
	v_fmac_f32_e32 v2, v159, v159
	v_fmac_f32_e32 v2, v160, v160
	v_fmac_f32_e32 v2, v161, v161
	v_add_f32_e32 v2, 0x358637bd, v2
	s_mov_b32 s2, 0x800000
	v_mul_f32_e32 v3, 0x4b800000, v2
	v_cmp_gt_f32_e32 vcc, s2, v2
	s_mov_b32 s26, 0
	s_nop 0
	v_cndmask_b32_e32 v2, v2, v3, vcc
	v_rsq_f32_e32 v2, v2
	v_cndmask_b32_e64 v3, 1.0, v231, s[44:45]
	v_mul_f32_e32 v5, 0x45800000, v2
	v_cndmask_b32_e32 v2, v2, v5, vcc
	v_mul_f32_e32 v2, v3, v2
	v_mov_b32_e32 v3, v2
.LBB0_372:
	ds_read2_b32 v[130:131], v4 offset1:1
	ds_read2_b32 v[132:133], v4 offset0:2 offset1:3
	ds_read2_b32 v[134:135], v4 offset0:4 offset1:5
	ds_read2_b32 v[136:137], v4 offset0:6 offset1:7
	ds_read2_b32 v[138:139], v4 offset0:8 offset1:9
	ds_read2_b32 v[140:141], v4 offset0:10 offset1:11
	ds_read2_b32 v[142:143], v4 offset0:12 offset1:13
	ds_read2_b32 v[144:145], v4 offset0:14 offset1:15
	s_waitcnt lgkmcnt(0)
	ds_read2_b32 v[146:147], v4 offset0:16 offset1:17
	ds_read2_b32 v[148:149], v4 offset0:18 offset1:19
	ds_read2_b32 v[150:151], v4 offset0:20 offset1:21
	ds_read2_b32 v[152:153], v4 offset0:22 offset1:23
	ds_read2_b32 v[154:155], v4 offset0:24 offset1:25
	ds_read2_b32 v[156:157], v4 offset0:26 offset1:27
	ds_read2_b32 v[158:159], v4 offset0:28 offset1:29
	ds_read2_b32 v[160:161], v4 offset0:30 offset1:31
	v_pk_mul_f32 v[130:131], v[2:3], v[130:131]
	v_pk_mul_f32 v[132:133], v[2:3], v[132:133]
	v_pk_mul_f32 v[134:135], v[2:3], v[134:135]
	v_pk_mul_f32 v[136:137], v[2:3], v[136:137]
	v_pk_mul_f32 v[138:139], v[2:3], v[138:139]
	v_pk_mul_f32 v[140:141], v[2:3], v[140:141]
	v_pk_mul_f32 v[142:143], v[2:3], v[142:143]
	v_pk_mul_f32 v[144:145], v[2:3], v[144:145]
	s_waitcnt lgkmcnt(0)
	ds_write2_b32 v4, v130, v131 offset1:1
	ds_write2_b32 v4, v132, v133 offset0:2 offset1:3
	ds_write2_b32 v4, v134, v135 offset0:4 offset1:5
	ds_write2_b32 v4, v136, v137 offset0:6 offset1:7
	ds_write2_b32 v4, v138, v139 offset0:8 offset1:9
	ds_write2_b32 v4, v140, v141 offset0:10 offset1:11
	ds_write2_b32 v4, v142, v143 offset0:12 offset1:13
	ds_write2_b32 v4, v144, v145 offset0:14 offset1:15
	s_waitcnt lgkmcnt(7)
	ds_read2_b32 v[130:131], v4 offset0:32 offset1:33
	ds_read2_b32 v[132:133], v4 offset0:34 offset1:35
	ds_read2_b32 v[134:135], v4 offset0:36 offset1:37
	ds_read2_b32 v[136:137], v4 offset0:38 offset1:39
	ds_read2_b32 v[138:139], v4 offset0:40 offset1:41
	ds_read2_b32 v[140:141], v4 offset0:42 offset1:43
	ds_read2_b32 v[142:143], v4 offset0:44 offset1:45
	ds_read2_b32 v[144:145], v4 offset0:46 offset1:47
	v_pk_mul_f32 v[146:147], v[2:3], v[146:147]
	v_pk_mul_f32 v[148:149], v[2:3], v[148:149]
	v_pk_mul_f32 v[150:151], v[2:3], v[150:151]
	v_pk_mul_f32 v[152:153], v[2:3], v[152:153]
	v_pk_mul_f32 v[154:155], v[2:3], v[154:155]
	v_pk_mul_f32 v[156:157], v[2:3], v[156:157]
	v_pk_mul_f32 v[158:159], v[2:3], v[158:159]
	v_pk_mul_f32 v[160:161], v[2:3], v[160:161]
	s_waitcnt lgkmcnt(0)
	ds_write2_b32 v4, v146, v147 offset0:16 offset1:17
	ds_write2_b32 v4, v148, v149 offset0:18 offset1:19
	ds_write2_b32 v4, v150, v151 offset0:20 offset1:21
	ds_write2_b32 v4, v152, v153 offset0:22 offset1:23
	ds_write2_b32 v4, v154, v155 offset0:24 offset1:25
	ds_write2_b32 v4, v156, v157 offset0:26 offset1:27
	ds_write2_b32 v4, v158, v159 offset0:28 offset1:29
	ds_write2_b32 v4, v160, v161 offset0:30 offset1:31
	s_waitcnt lgkmcnt(7)
	ds_read2_b32 v[146:147], v4 offset0:48 offset1:49
	ds_read2_b32 v[148:149], v4 offset0:50 offset1:51
	ds_read2_b32 v[150:151], v4 offset0:52 offset1:53
	ds_read2_b32 v[152:153], v4 offset0:54 offset1:55
	ds_read2_b32 v[154:155], v4 offset0:56 offset1:57
	ds_read2_b32 v[156:157], v4 offset0:58 offset1:59
	ds_read2_b32 v[158:159], v4 offset0:60 offset1:61
	ds_read2_b32 v[160:161], v4 offset0:62 offset1:63
	v_pk_mul_f32 v[130:131], v[2:3], v[130:131]
	v_pk_mul_f32 v[132:133], v[2:3], v[132:133]
	v_pk_mul_f32 v[134:135], v[2:3], v[134:135]
	v_pk_mul_f32 v[136:137], v[2:3], v[136:137]
	v_pk_mul_f32 v[138:139], v[2:3], v[138:139]
	v_pk_mul_f32 v[140:141], v[2:3], v[140:141]
	v_pk_mul_f32 v[142:143], v[2:3], v[142:143]
	v_pk_mul_f32 v[144:145], v[2:3], v[144:145]
	s_waitcnt lgkmcnt(0)
	ds_write2_b32 v4, v130, v131 offset0:32 offset1:33
	ds_write2_b32 v4, v132, v133 offset0:34 offset1:35
	ds_write2_b32 v4, v134, v135 offset0:36 offset1:37
	ds_write2_b32 v4, v136, v137 offset0:38 offset1:39
	ds_write2_b32 v4, v138, v139 offset0:40 offset1:41
	ds_write2_b32 v4, v140, v141 offset0:42 offset1:43
	ds_write2_b32 v4, v142, v143 offset0:44 offset1:45
	ds_write2_b32 v4, v144, v145 offset0:46 offset1:47
	v_pk_mul_f32 v[146:147], v[2:3], v[146:147]
	v_pk_mul_f32 v[148:149], v[2:3], v[148:149]
	v_pk_mul_f32 v[150:151], v[2:3], v[150:151]
	v_pk_mul_f32 v[152:153], v[2:3], v[152:153]
	v_pk_mul_f32 v[154:155], v[2:3], v[154:155]
	v_pk_mul_f32 v[156:157], v[2:3], v[156:157]
	v_pk_mul_f32 v[158:159], v[2:3], v[158:159]
	v_pk_mul_f32 v[160:161], v[2:3], v[160:161]
	s_waitcnt lgkmcnt(0)
	ds_write2_b32 v4, v146, v147 offset0:48 offset1:49
	ds_write2_b32 v4, v148, v149 offset0:50 offset1:51
	ds_write2_b32 v4, v150, v151 offset0:52 offset1:53
	ds_write2_b32 v4, v152, v153 offset0:54 offset1:55
	ds_write2_b32 v4, v154, v155 offset0:56 offset1:57
	ds_write2_b32 v4, v156, v157 offset0:58 offset1:59
	ds_write2_b32 v4, v158, v159 offset0:60 offset1:61
	ds_write2_b32 v4, v160, v161 offset0:62 offset1:63
